# attention: exp block + row max interleaved into P.V MFMAs (scalar fma prescale), exp results in free regs
# speedup vs baseline: 1.0668x; 1.0031x over previous
.LBB0_214:
	s_mov_b32 s100, 0x3e38aa3b
	s_mov_b32 s101, 0x3e38aa3b
	s_lshl_b32 s4, s15, 2
	s_and_b32 s4, s4, 8
	v_readlane_b32 s5, v249, 53
	s_or_b32 s5, s4, s5
	s_lshl_b32 s4, s15, 5
	s_and_b32 s4, s4, 32
	v_readlane_b32 s6, v249, 62
	s_add_i32 s4, s4, s6
	v_mov_b64_e32 v[0:1], v[132:133]
	s_lshr_b32 s6, s5, 2
	v_mov_b32_e32 v18, v154
	s_lshl_b32 s7, s5, 11
	s_ashr_i32 s5, s4, 31
	v_lshl_add_u64 v[140:141], v[0:1], 0, s[22:23]
	s_lshl_b64 s[4:5], s[4:5], 7
	v_ashrrev_i32_e32 v173, 7, v18
	v_and_b32_e32 v0, 0x3fffffc0, v18
	v_lshl_add_u32 v174, v0, 2, s79
	s_add_u32 s4, s7, s4
	v_lshlrev_b32_e32 v0, 5, v173
	s_addc_u32 s5, 0, s5
	v_ashrrev_i32_e32 v1, 31, v0
	v_and_b32_e32 v138, 31, v18
	v_lshl_add_u64 v[142:143], s[4:5], 0, v[0:1]
	v_or_b32_e32 v0, v142, v138
	v_mad_u64_u32 v[0:1], s[4:5], v0, s50, v[140:141]
	s_mul_i32 s52, s6, 0x3600000
	v_readlane_b32 s4, v249, 54
	v_bfe_u32 v172, v18, 6, 1
	v_lshl_add_u64 v[2:3], v[140:141], 0, s[52:53]
	v_mad_i32_i24 v1, v143, s50, v1
	s_lshl_b32 s52, s4, 1
	v_bfe_u32 v170, v18, 5, 1
	v_lshl_add_u64 v[0:1], v[0:1], 0, s[52:53]
	v_lshlrev_b32_e32 v134, 7, v172
	v_lshl_add_u64 v[0:1], v[0:1], 0, v[134:135]
	v_lshlrev_b32_e32 v144, 4, v170
	v_mov_b32_e32 v145, v135
	v_ashrrev_i32_e32 v19, 4, v18
	v_lshl_add_u64 v[0:1], v[0:1], 0, v[144:145]
	v_and_b32_e32 v4, 0xfffff0, v19
	v_lshlrev_b32_e32 v5, 1, v19
	global_load_dwordx4 v[108:111], v[0:1], off
	global_load_dwordx4 v[104:107], v[0:1], off offset:32
	global_load_dwordx4 v[100:103], v[0:1], off offset:64
	global_load_dwordx4 v[96:99], v[0:1], off offset:96
	v_lshlrev_b32_e32 v0, 3, v18
	v_and_or_b32 v4, v5, 8, v4
	v_lshrrev_b32_e32 v4, 1, v4
	v_bfe_u32 v6, v0, 5, 2
	v_and_b32_e32 v1, 0x78, v0
	v_or_b32_e32 v0, v4, v6
	v_lshrrev_b32_e32 v5, 1, v19
	v_lshlrev_b32_e32 v4, 9, v0
	v_and_b32_e32 v0, 3, v19
	v_and_or_b32 v0, v5, 4, v0
	v_add_u32_e32 v20, 32, v19
	v_lshlrev_b32_e32 v5, 6, v0
	v_lshlrev_b32_e32 v0, 1, v1
	v_and_b32_e32 v1, 0xfffff0, v20
	v_lshlrev_b32_e32 v7, 1, v20
	v_and_or_b32 v1, v7, 8, v1
	v_and_b32_e32 v171, 63, v18
	v_lshrrev_b32_e32 v1, 1, v1
	v_lshlrev_b32_e32 v7, 4, v18
	v_or_b32_e32 v1, v1, v6
	v_lshlrev_b32_e32 v6, 3, v171
	v_and_b32_e32 v8, 0xc0, v7
	v_lshlrev_b32_e32 v9, 1, v18
	v_and_or_b32 v8, v6, 24, v8
	v_and_b32_e32 v9, 32, v9
	v_and_b32_e32 v6, 0x100, v6
	v_or3_b32 v48, v8, v9, v6
	v_or_b32_e32 v8, v134, v144
	v_lshlrev_b32_e32 v6, 8, v138
	v_and_b32_e32 v7, 0x70, v7
	v_or_b32_e32 v9, 32, v8
	v_bitop3_b32 v21, v8, v6, v7 bitop3:0xde
	v_xad_u32 v50, v9, v7, v6
	v_or_b32_e32 v9, 64, v8
	v_or_b32_e32 v8, 0x60, v8
	v_lshlrev_b32_e32 v1, 9, v1
	v_xad_u32 v58, v9, v7, v6
	v_xad_u32 v49, v8, v7, v6
	v_lshl_add_u64 v[2:3], v[2:3], 0, s[52:53]
	v_and_b32_e32 v6, 48, v0
	v_or3_b32 v23, v1, v5, v6
	v_mad_i64_i32 v[2:3], s[4:5], v19, s50, v[2:3]
	v_mov_b32_e32 v1, v135
	v_lshl_add_u64 v[2:3], v[2:3], 0, v[0:1]
	s_mov_b64 s[4:5], 0x400
	v_lshl_add_u64 v[146:147], v[2:3], 0, s[4:5]
	s_mov_b64 s[4:5], 0x36400
	v_lshl_add_u64 v[148:149], v[2:3], 0, s[4:5]
	v_or3_b32 v22, v4, v5, v6
	global_load_dwordx4 v[2:5], v[146:147], off offset:1024
	global_load_dwordx4 v[6:9], v[148:149], off offset:1024
	global_load_dwordx4 v[10:13], v[146:147], off
	global_load_dwordx4 v[14:17], v[148:149], off
	v_add_u32_e32 v134, 0, v22
	s_waitcnt vmcnt(0)
	v_lshlrev_b32_e32 v1, 8, v19
	v_add_u32_e32 v145, 0, v23
	v_add_u32_e32 v181, 0, v21
	v_add_u32_e32 v182, 0, v50
	v_add_u32_e32 v183, 0, v58
	v_add_u32_e32 v184, 0, v49
	s_cmp_lg_u32 0, -1
	s_cselect_b32 s6, 0, 0
	s_mov_b32 s4, 0x6c000
	s_mov_b32 s57, s56
	s_mov_b32 s58, s56
	s_mov_b32 s59, s56
	s_mov_b32 s60, s56
	s_mov_b32 s61, s56
	s_mov_b32 s62, s56
	s_mov_b32 s63, s56
	s_mov_b32 s64, s56
	s_mov_b32 s65, s56
	s_mov_b32 s66, s56
	s_mov_b32 s67, s56
	s_mov_b32 s68, s56
	s_mov_b32 s69, s56
	s_mov_b32 s70, s56
	s_mov_b32 s71, s56
	v_add_u32_e32 v177, s6, v48
	v_lshl_add_u32 v176, v138, 2, v174
	v_mov_b32_e32 v178, 0
	s_waitcnt vmcnt(3)
	ds_write_b128 v134, v[2:5]
	v_and_b32_e32 v2, 0x70, v18
	v_bitop3_b32 v1, v0, v1, v2 bitop3:0xde
	v_add_u32_e32 v175, 0, v1
	v_lshlrev_b32_e32 v1, 8, v20
	v_bitop3_b32 v0, v0, v1, v2 bitop3:0xde
	v_add_u32_e32 v180, 0, v0
	s_waitcnt vmcnt(2)
	ds_write_b128 v145, v[6:9]
	s_waitcnt vmcnt(1)
	ds_write_b128 v175, v[10:13] offset:32768
	s_waitcnt vmcnt(0)
	ds_write_b128 v180, v[14:17] offset:32768
	s_waitcnt lgkmcnt(0)
	s_barrier
	ds_read_b128 v[16:19], v181 offset:32768
	ds_read_b128 v[20:23], v181 offset:40960
	s_waitcnt lgkmcnt(1)
	v_mfma_f32_32x32x16_bf16 v[32:47], v[16:19], v[108:111], 0
	ds_read_b128 v[50:53], v182 offset:32768
	ds_read_b128 v[54:57], v182 offset:40960
	v_mov_b64_e32 v[0:1], s[56:57]
	v_mov_b64_e32 v[14:15], s[70:71]
	v_mov_b64_e32 v[2:3], s[58:59]
	v_mov_b64_e32 v[4:5], s[60:61]
	v_mov_b64_e32 v[6:7], s[62:63]
	v_mov_b64_e32 v[8:9], s[64:65]
	s_waitcnt lgkmcnt(2)
	v_mfma_f32_32x32x16_bf16 v[16:31], v[20:23], v[108:111], 0
	v_mov_b64_e32 v[10:11], s[66:67]
	v_mov_b64_e32 v[12:13], s[68:69]
	s_mov_b32 s57, -1
	s_mov_b64 s[58:59], 0
	s_waitcnt lgkmcnt(1)
	v_mfma_f32_32x32x16_bf16 v[32:47], v[50:53], v[104:107], v[32:47]
	s_waitcnt lgkmcnt(0)
	v_mfma_f32_32x32x16_bf16 v[16:31], v[54:57], v[104:107], v[16:31]
	ds_read_b128 v[50:53], v183 offset:32768
	ds_read_b128 v[54:57], v183 offset:40960
	s_waitcnt lgkmcnt(1)
	v_mfma_f32_32x32x16_bf16 v[32:47], v[50:53], v[100:103], v[32:47]
	s_waitcnt lgkmcnt(0)
	v_mfma_f32_32x32x16_bf16 v[16:31], v[54:57], v[100:103], v[16:31]
	ds_read_b128 v[50:53], v184 offset:32768
	ds_read_b128 v[54:57], v184 offset:40960
	s_waitcnt lgkmcnt(1)
	v_mfma_f32_32x32x16_bf16 v[32:47], v[50:53], v[96:99], v[32:47]
	s_waitcnt lgkmcnt(0)
	v_mfma_f32_32x32x16_bf16 v[16:31], v[54:57], v[96:99], v[16:31]
	s_nop 9
	v_max_f32_e32 v49, v33, v33
	v_max_f32_e32 v50, v32, v32
	v_max_f32_e32 v49, v50, v49
	v_max3_f32 v49, v49, v34, v35
	v_max3_f32 v49, v49, v36, v37
	v_max3_f32 v49, v49, v38, v39
	v_max3_f32 v49, v49, v40, v41
	v_max3_f32 v49, v49, v42, v43
	v_max3_f32 v49, v49, v44, v45
	v_max3_f32 v49, v49, v46, v47
	v_max3_f32 v49, v49, v16, v17
	v_max3_f32 v49, v49, v18, v19
	v_max3_f32 v49, v49, v20, v21
	v_max3_f32 v49, v49, v22, v23
	v_max3_f32 v49, v49, v24, v25
	v_max3_f32 v49, v49, v26, v27
	v_max3_f32 v49, v49, v28, v29
	v_max3_f32 v49, v49, v30, v31
	v_mov_b32_e32 v50, v49
	s_nop 1
	v_permlane32_swap_b32_e32 v49, v50
	v_max_f32_e32 v50, v50, v50
	v_max_f32_e32 v49, v49, v49
	v_max_f32_e32 v49, v49, v50
	v_add_f32_e32 v50, 0x7149f2ca, v49
	v_cmp_ge_f32_e32 vcc, s33, v50
	s_cmp_eq_u64 vcc, exec
	s_cselect_b64 vcc, -1, 0
	v_max_f32_e32 v49, 0xf149f2ca, v49
	v_cndmask_b32_e32 v186, v49, v164, vcc
	v_sub_f32_e32 v50, 0xf149f2ca, v49
	v_mul_f32_e32 v49, 0xbe38aa3b, v186
	v_fmamk_f32 v32, v32, 0x3e38aa3b, v49
	v_fmamk_f32 v16, v16, 0x3e38aa3b, v49
	v_exp_f32_e32 v129, v32
	v_fmamk_f32 v32, v33, 0x3e38aa3b, v49
	v_exp_f32_e32 v120, v16
	v_fmamk_f32 v16, v17, 0x3e38aa3b, v49
	v_exp_f32_e32 v131, v32
	v_fmamk_f32 v32, v34, 0x3e38aa3b, v49
	v_exp_f32_e32 v122, v16
	v_fmamk_f32 v16, v18, 0x3e38aa3b, v49
	v_exp_f32_e32 v130, v32
	v_fmamk_f32 v32, v35, 0x3e38aa3b, v49
	v_exp_f32_e32 v121, v16
	v_fmamk_f32 v16, v19, 0x3e38aa3b, v49
	v_exp_f32_e32 v198, v32
	v_fmamk_f32 v32, v36, 0x3e38aa3b, v49
	v_exp_f32_e32 v124, v16
	v_fmamk_f32 v16, v20, 0x3e38aa3b, v49
	v_exp_f32_e32 v197, v32
	v_fmamk_f32 v32, v37, 0x3e38aa3b, v49
	v_exp_f32_e32 v123, v16
	v_fmamk_f32 v16, v21, 0x3e38aa3b, v49
	v_mul_f32_e32 v50, 0x3e38aa3b, v50
	v_exp_f32_e32 v200, v32
	v_fmamk_f32 v32, v38, 0x3e38aa3b, v49
	v_exp_f32_e32 v126, v16
	v_fmamk_f32 v16, v22, 0x3e38aa3b, v49
	v_exp_f32_e32 v50, v50
	v_exp_f32_e32 v199, v32
	v_fmamk_f32 v32, v39, 0x3e38aa3b, v49
	v_exp_f32_e32 v125, v16
	v_fmamk_f32 v16, v23, 0x3e38aa3b, v49
	v_exp_f32_e32 v201, v32
	v_fmamk_f32 v32, v40, 0x3e38aa3b, v49
	v_exp_f32_e32 v127, v16
	v_fmamk_f32 v16, v24, 0x3e38aa3b, v49
	v_exp_f32_e32 v189, v32
	v_fmamk_f32 v32, v41, 0x3e38aa3b, v49
	v_exp_f32_e32 v112, v16
	v_fmamk_f32 v16, v25, 0x3e38aa3b, v49
	v_exp_f32_e32 v192, v32
	v_fmamk_f32 v32, v42, 0x3e38aa3b, v49
	v_exp_f32_e32 v114, v16
	v_fmamk_f32 v16, v26, 0x3e38aa3b, v49
	v_cndmask_b32_e64 v185, v50, 1.0, vcc
	v_exp_f32_e32 v190, v32
	v_fmamk_f32 v32, v43, 0x3e38aa3b, v49
	v_exp_f32_e32 v113, v16
	v_fmamk_f32 v16, v27, 0x3e38aa3b, v49
	v_add_co_u32_e32 v24, vcc, s4, v146
	v_exp_f32_e32 v194, v32
	v_fmamk_f32 v32, v44, 0x3e38aa3b, v49
	v_exp_f32_e32 v116, v16
	v_fmamk_f32 v16, v28, 0x3e38aa3b, v49
	v_addc_co_u32_e32 v25, vcc, 0, v147, vcc
	v_exp_f32_e32 v193, v32
	v_fmamk_f32 v32, v45, 0x3e38aa3b, v49
	v_exp_f32_e32 v115, v16
	v_fmamk_f32 v16, v29, 0x3e38aa3b, v49
	v_add_co_u32_e32 v28, vcc, s4, v148
	v_exp_f32_e32 v196, v32
	v_fmamk_f32 v32, v46, 0x3e38aa3b, v49
	v_exp_f32_e32 v118, v16
	v_fmamk_f32 v16, v30, 0x3e38aa3b, v49
	v_addc_co_u32_e32 v29, vcc, 0, v149, vcc
	v_exp_f32_e32 v191, v32
	v_fmamk_f32 v32, v47, 0x3e38aa3b, v49
	v_exp_f32_e32 v117, v16
	v_fmac_f32_e32 v49, 0x3e38aa3b, v31
	global_load_dwordx4 v[16:19], v[24:25], off offset:1024
	global_load_dwordx4 v[20:23], v[28:29], off offset:1024
	s_nop 0
	global_load_dwordx4 v[24:27], v[24:25], off
	s_nop 0
	global_load_dwordx4 v[28:31], v[28:29], off
	v_exp_f32_e32 v195, v32
	v_exp_f32_e32 v119, v49
	s_waitcnt vmcnt(0)
	s_addk_i32 s6, 0x4000
	s_waitcnt vmcnt(3)
	ds_write_b128 v134, v[16:19] offset:16384
	s_waitcnt vmcnt(2)
	ds_write_b128 v145, v[20:23] offset:16384
	s_waitcnt vmcnt(1)
	ds_write_b128 v175, v[24:27] offset:49152
	s_waitcnt vmcnt(0)
	ds_write_b128 v180, v[28:31] offset:49152
	v_add_u32_e32 v179, s6, v48
	v_mov_b64_e32 v[62:63], v[14:15]
	v_mov_b64_e32 v[46:47], v[14:15]
	v_mov_b64_e32 v[30:31], v[14:15]
	v_cmp_gt_u32_e64 s[4:5], 32, v171
	v_mov_b64_e32 v[60:61], v[12:13]
	v_mov_b64_e32 v[58:59], v[10:11]
	v_mov_b64_e32 v[56:57], v[8:9]
	v_mov_b64_e32 v[54:55], v[6:7]
	v_mov_b64_e32 v[52:53], v[4:5]
	v_mov_b64_e32 v[50:51], v[2:3]
	v_mov_b64_e32 v[48:49], v[0:1]
	v_mov_b64_e32 v[44:45], v[12:13]
	v_mov_b64_e32 v[42:43], v[10:11]
	v_mov_b64_e32 v[40:41], v[8:9]
	v_mov_b64_e32 v[38:39], v[6:7]
	v_mov_b64_e32 v[36:37], v[4:5]
	v_mov_b64_e32 v[34:35], v[2:3]
	v_mov_b64_e32 v[32:33], v[0:1]
	v_mov_b64_e32 v[28:29], v[12:13]
	v_mov_b64_e32 v[26:27], v[10:11]
	v_mov_b64_e32 v[24:25], v[8:9]
	v_mov_b64_e32 v[22:23], v[6:7]
	v_mov_b64_e32 v[20:21], v[4:5]
	v_mov_b64_e32 v[18:19], v[2:3]
	v_mov_b64_e32 v[16:17], v[0:1]
	s_waitcnt lgkmcnt(0)
	s_barrier
	v_mov_b32_e32 v226, v112
	v_mov_b32_e32 v228, v113
	v_mov_b32_e32 v227, v114
	v_mov_b32_e32 v230, v115
	v_mov_b32_e32 v229, v116
	v_mov_b32_e32 v232, v117
	v_mov_b32_e32 v231, v118
	v_mov_b32_e32 v233, v119
	v_mov_b32_e32 v218, v120
	v_mov_b32_e32 v220, v121
	v_mov_b32_e32 v219, v122
	v_mov_b32_e32 v222, v123
	v_mov_b32_e32 v221, v124
	v_mov_b32_e32 v224, v125
	v_mov_b32_e32 v223, v126
	v_mov_b32_e32 v225, v127
	v_mov_b32_e32 v234, v129
	v_mov_b32_e32 v236, v130
	v_mov_b32_e32 v235, v131
	v_mov_b32_e32 v242, v189
	v_mov_b32_e32 v244, v190
	v_mov_b32_e32 v252, v191
	v_mov_b32_e32 v243, v192
	v_mov_b32_e32 v246, v193
	v_mov_b32_e32 v245, v194
	v_mov_b32_e32 v253, v195
	v_mov_b32_e32 v247, v196
	v_mov_b32_e32 v238, v197
	v_mov_b32_e32 v237, v198
	v_mov_b32_e32 v240, v199
	v_mov_b32_e32 v239, v200
	v_mov_b32_e32 v241, v201
.LBB0_215:
	v_lshl_add_u64 v[150:151], v[148:149], 0, s[58:59]
	ds_read_b128 v[64:67], v181 offset:49152
	ds_read_b128 v[68:71], v181 offset:57344
	v_add_f32_e32 v128, 0, v234
	v_add_f32_e32 v128, v235, v128
	v_add_f32_e32 v128, v236, v128
	s_waitcnt lgkmcnt(1)
	v_mfma_f32_32x32x16_bf16 v[80:95], v[64:67], v[108:111], 0
	v_add_f32_e32 v128, v237, v128
	v_add_f32_e32 v128, v238, v128
	ds_read_b128 v[202:205], v182 offset:49152
	ds_read_b128 v[206:209], v182 offset:57344
	v_add_f32_e32 v128, v239, v128
	v_add_f32_e32 v128, v240, v128
	v_add_f32_e32 v128, v241, v128
	v_add_f32_e32 v128, v242, v128
	s_waitcnt lgkmcnt(2)
	v_mfma_f32_32x32x16_bf16 v[64:79], v[68:71], v[108:111], 0
	v_add_f32_e32 v128, v243, v128
	v_add_f32_e32 v128, v244, v128
	v_add_f32_e32 v128, v245, v128
	v_add_f32_e32 v128, v246, v128
	v_add_f32_e32 v128, v247, v128
	v_add_f32_e32 v128, v252, v128
	v_add_f32_e32 v128, v253, v128
	s_waitcnt lgkmcnt(1)
	v_mfma_f32_32x32x16_bf16 v[80:95], v[202:205], v[104:107], v[80:95]
	v_add_f32_e32 v128, v218, v128
	v_add_f32_e32 v128, v219, v128
	v_add_f32_e32 v128, v220, v128
	v_add_f32_e32 v128, v221, v128
	v_add_f32_e32 v128, v222, v128
	v_add_f32_e32 v128, v223, v128
	v_add_f32_e32 v128, v224, v128
	s_waitcnt lgkmcnt(0)
	v_mfma_f32_32x32x16_bf16 v[64:79], v[206:209], v[104:107], v[64:79]
	ds_read_b128 v[202:205], v183 offset:49152
	ds_read_b128 v[206:209], v183 offset:57344
	v_add_f32_e32 v128, v225, v128
	v_add_f32_e32 v128, v226, v128
	v_add_f32_e32 v128, v227, v128
	v_add_f32_e32 v128, v228, v128
	v_add_f32_e32 v128, v229, v128
	v_add_f32_e32 v128, v230, v128
	s_waitcnt lgkmcnt(1)
	v_mfma_f32_32x32x16_bf16 v[80:95], v[202:205], v[100:103], v[80:95]
	v_add_f32_e32 v128, v231, v128
	v_add_f32_e32 v128, v232, v128
	v_add_f32_e32 v187, v233, v128
	v_mov_b32_e32 v188, v187
	v_lshl_add_u64 v[152:153], v[146:147], 0, s[58:59]
	s_nop 0
	v_permlane32_swap_b32_e32 v187, v188
	s_waitcnt lgkmcnt(0)
	v_mfma_f32_32x32x16_bf16 v[64:79], v[206:209], v[100:103], v[64:79]
	ds_read_b128 v[202:205], v184 offset:49152
	ds_read_b128 v[206:209], v184 offset:57344
	v_cvt_pk_bf16_f32 v128, v234, v235
	v_cvt_pk_bf16_f32 v129, v236, v237
	v_cvt_pk_bf16_f32 v130, v238, v239
	v_cvt_pk_bf16_f32 v131, v240, v241
	v_cvt_pk_bf16_f32 v198, v242, v243
	v_cvt_pk_bf16_f32 v199, v244, v245
	s_waitcnt lgkmcnt(1)
	v_mfma_f32_32x32x16_bf16 v[80:95], v[202:205], v[96:99], v[80:95]
	v_permlane32_swap_b32_e32 v128, v130
	v_cvt_pk_bf16_f32 v200, v246, v247
	v_cvt_pk_bf16_f32 v201, v252, v253
	v_cvt_pk_bf16_f32 v190, v218, v219
	v_cvt_pk_bf16_f32 v191, v220, v221
	v_cvt_pk_bf16_f32 v192, v222, v223
	s_waitcnt lgkmcnt(0)
	v_mfma_f32_32x32x16_bf16 v[64:79], v[206:209], v[96:99], v[64:79]
	v_cvt_pk_bf16_f32 v193, v224, v225
	v_cvt_pk_bf16_f32 v194, v226, v227
	v_cvt_pk_bf16_f32 v195, v228, v229
	v_cvt_pk_bf16_f32 v196, v230, v231
	v_cvt_pk_bf16_f32 v197, v232, v233
	v_permlane32_swap_b32_e32 v129, v131
	v_permlane32_swap_b32_e32 v198, v200
	v_permlane32_swap_b32_e32 v199, v201
	v_permlane32_swap_b32_e32 v190, v192
	v_permlane32_swap_b32_e32 v191, v193
	v_permlane32_swap_b32_e32 v194, v196
	v_permlane32_swap_b32_e32 v195, v197
	v_add_co_u32_e32 v116, vcc, s86, v152
	s_nop 1
	v_addc_co_u32_e32 v117, vcc, 0, v153, vcc
	v_add_co_u32_e32 v120, vcc, s86, v150
	s_nop 1
	v_addc_co_u32_e32 v121, vcc, 0, v151, vcc
	global_load_dwordx4 v[112:115], v[116:117], off offset:1024
	s_nop 0
	global_load_dwordx4 v[116:119], v[116:117], off
	s_nop 0
	global_load_dwordx4 v[124:127], v[120:121], off offset:1024
	s_nop 0
	global_load_dwordx4 v[120:123], v[120:121], off
	ds_read_b64_tr_b16 v[202:203], v177 offset:0
	ds_read_b64_tr_b16 v[204:205], v177 offset:0x800
	ds_read_b64_tr_b16 v[206:207], v177 offset:0x1000
	ds_read_b64_tr_b16 v[208:209], v177 offset:0x1800
	ds_read_b64_tr_b16 v[210:211], v177 offset:0x2000
	ds_read_b64_tr_b16 v[212:213], v177 offset:0x2800
	ds_read_b64_tr_b16 v[214:215], v177 offset:0x3000
	ds_read_b64_tr_b16 v[216:217], v177 offset:0x3800
	s_waitcnt lgkmcnt(0)
	s_nop 0
	v_mfma_f32_32x32x16_bf16 v[0:15], v[128:131], v[202:205], v[0:15]
	ds_read_b64_tr_b16 v[202:203], v177 offset:0x200
	ds_read_b64_tr_b16 v[204:205], v177 offset:0xa00
	v_max_f32_e32 v250, v81, v81
	v_max_f32_e32 v251, v80, v80
	v_max_f32_e32 v250, v251, v250
	v_max3_f32 v250, v250, v82, v83
	v_max3_f32 v250, v250, v84, v85
	v_max3_f32 v250, v250, v86, v87
	v_max3_f32 v250, v250, v88, v89
	v_max3_f32 v250, v250, v90, v91
	v_max3_f32 v250, v250, v92, v93
	v_mfma_f32_32x32x16_bf16 v[0:15], v[198:201], v[206:209], v[0:15]
	ds_read_b64_tr_b16 v[206:207], v177 offset:0x1200
	ds_read_b64_tr_b16 v[208:209], v177 offset:0x1a00
	v_max3_f32 v250, v250, v94, v95
	v_max3_f32 v250, v250, v64, v65
	v_max3_f32 v250, v250, v66, v67
	v_max3_f32 v250, v250, v68, v69
	v_max3_f32 v250, v250, v70, v71
	v_max3_f32 v250, v250, v72, v73
	v_max3_f32 v250, v250, v74, v75
	v_max3_f32 v250, v250, v76, v77
	v_max3_f32 v250, v250, v78, v79
	v_mfma_f32_32x32x16_bf16 v[0:15], v[190:193], v[210:213], v[0:15]
	ds_read_b64_tr_b16 v[210:211], v177 offset:0x2200
	ds_read_b64_tr_b16 v[212:213], v177 offset:0x2a00
	v_mov_b32_e32 v251, v250
	s_nop 1
	v_permlane32_swap_b32_e32 v250, v251
	v_max_f32_e32 v251, v251, v251
	v_max_f32_e32 v250, v250, v250
	v_max_f32_e32 v250, v250, v251
	v_sub_f32_e32 v251, v250, v186
	v_cmp_ge_f32_e32 vcc, s33, v251
	v_max_f32_e32 v251, v186, v186
	v_max_f32_e32 v250, v251, v250
	v_mfma_f32_32x32x16_bf16 v[0:15], v[194:197], v[214:217], v[0:15]
	ds_read_b64_tr_b16 v[214:215], v177 offset:0x3200
	ds_read_b64_tr_b16 v[216:217], v177 offset:0x3a00
	v_sub_f32_e32 v251, v186, v250
	v_mul_f32_e32 v251, 0x3e38aa3b, v251
	v_exp_f32_e32 v251, v251
	s_cmp_eq_u64 vcc, exec
	s_cselect_b64 s[6:7], -1, 0
	v_cndmask_b32_e64 v186, v250, v186, s[6:7]
	v_mul_f32_e32 v254, 0xbe38aa3b, v186
	s_waitcnt lgkmcnt(0)
	v_mfma_f32_32x32x16_bf16 v[48:63], v[128:131], v[202:205], v[48:63]
	ds_read_b64_tr_b16 v[202:203], v177 offset:0x400
	ds_read_b64_tr_b16 v[204:205], v177 offset:0xc00
	v_fmamk_f32 v80, v80, 0x3e38aa3b, v254
	v_fmamk_f32 v81, v81, 0x3e38aa3b, v254
	v_fmamk_f32 v64, v64, 0x3e38aa3b, v254
	v_fmamk_f32 v65, v65, 0x3e38aa3b, v254
	v_exp_f32_e32 v234, v80
	v_exp_f32_e32 v235, v81
	v_fmamk_f32 v82, v82, 0x3e38aa3b, v254
	v_fmamk_f32 v83, v83, 0x3e38aa3b, v254
	v_mfma_f32_32x32x16_bf16 v[48:63], v[198:201], v[206:209], v[48:63]
	ds_read_b64_tr_b16 v[206:207], v177 offset:0x1400
	ds_read_b64_tr_b16 v[208:209], v177 offset:0x1c00
	v_exp_f32_e32 v218, v64
	v_exp_f32_e32 v219, v65
	v_fmamk_f32 v66, v66, 0x3e38aa3b, v254
	v_fmamk_f32 v67, v67, 0x3e38aa3b, v254
	v_exp_f32_e32 v236, v82
	v_mfma_f32_32x32x16_bf16 v[48:63], v[190:193], v[210:213], v[48:63]
	ds_read_b64_tr_b16 v[210:211], v177 offset:0x2400
	ds_read_b64_tr_b16 v[212:213], v177 offset:0x2c00
	v_exp_f32_e32 v237, v83
	v_fmamk_f32 v84, v84, 0x3e38aa3b, v254
	v_fmamk_f32 v85, v85, 0x3e38aa3b, v254
	v_exp_f32_e32 v220, v66
	v_exp_f32_e32 v221, v67
	v_mfma_f32_32x32x16_bf16 v[48:63], v[194:197], v[214:217], v[48:63]
	ds_read_b64_tr_b16 v[214:215], v177 offset:0x3400
	ds_read_b64_tr_b16 v[216:217], v177 offset:0x3c00
	v_fmamk_f32 v68, v68, 0x3e38aa3b, v254
	v_fmamk_f32 v69, v69, 0x3e38aa3b, v254
	v_exp_f32_e32 v238, v84
	v_exp_f32_e32 v239, v85
	v_fmamk_f32 v86, v86, 0x3e38aa3b, v254
	v_fmamk_f32 v87, v87, 0x3e38aa3b, v254
	s_waitcnt lgkmcnt(0)
	v_mfma_f32_32x32x16_bf16 v[32:47], v[128:131], v[202:205], v[32:47]
	ds_read_b64_tr_b16 v[202:203], v177 offset:0x600
	ds_read_b64_tr_b16 v[204:205], v177 offset:0xe00
	v_exp_f32_e32 v222, v68
	v_exp_f32_e32 v223, v69
	v_fmamk_f32 v70, v70, 0x3e38aa3b, v254
	v_fmamk_f32 v71, v71, 0x3e38aa3b, v254
	v_exp_f32_e32 v240, v86
	v_mfma_f32_32x32x16_bf16 v[32:47], v[198:201], v[206:209], v[32:47]
	ds_read_b64_tr_b16 v[206:207], v177 offset:0x1600
	ds_read_b64_tr_b16 v[208:209], v177 offset:0x1e00
	v_exp_f32_e32 v241, v87
	v_fmamk_f32 v88, v88, 0x3e38aa3b, v254
	v_fmamk_f32 v89, v89, 0x3e38aa3b, v254
	v_exp_f32_e32 v224, v70
	v_exp_f32_e32 v225, v71
	v_mfma_f32_32x32x16_bf16 v[32:47], v[190:193], v[210:213], v[32:47]
	ds_read_b64_tr_b16 v[210:211], v177 offset:0x2600
	ds_read_b64_tr_b16 v[212:213], v177 offset:0x2e00
	v_fmamk_f32 v72, v72, 0x3e38aa3b, v254
	v_fmamk_f32 v73, v73, 0x3e38aa3b, v254
	v_exp_f32_e32 v242, v88
	v_exp_f32_e32 v243, v89
	v_fmamk_f32 v90, v90, 0x3e38aa3b, v254
	v_fmamk_f32 v91, v91, 0x3e38aa3b, v254
	v_mfma_f32_32x32x16_bf16 v[32:47], v[194:197], v[214:217], v[32:47]
	ds_read_b64_tr_b16 v[214:215], v177 offset:0x3600
	ds_read_b64_tr_b16 v[216:217], v177 offset:0x3e00
	v_exp_f32_e32 v226, v72
	v_exp_f32_e32 v227, v73
	v_fmamk_f32 v74, v74, 0x3e38aa3b, v254
	v_fmamk_f32 v75, v75, 0x3e38aa3b, v254
	v_exp_f32_e32 v244, v90
	s_waitcnt lgkmcnt(0)
	v_mfma_f32_32x32x16_bf16 v[16:31], v[128:131], v[202:205], v[16:31]
	v_exp_f32_e32 v245, v91
	v_fmamk_f32 v92, v92, 0x3e38aa3b, v254
	v_fmamk_f32 v93, v93, 0x3e38aa3b, v254
	v_exp_f32_e32 v228, v74
	v_exp_f32_e32 v229, v75
	v_mfma_f32_32x32x16_bf16 v[16:31], v[198:201], v[206:209], v[16:31]
	v_fmamk_f32 v76, v76, 0x3e38aa3b, v254
	v_fmamk_f32 v77, v77, 0x3e38aa3b, v254
	v_exp_f32_e32 v246, v92
	v_exp_f32_e32 v247, v93
	v_fmamk_f32 v94, v94, 0x3e38aa3b, v254
	v_fmamk_f32 v95, v95, 0x3e38aa3b, v254
	v_mfma_f32_32x32x16_bf16 v[16:31], v[190:193], v[210:213], v[16:31]
	v_exp_f32_e32 v230, v76
	v_exp_f32_e32 v231, v77
	v_fmamk_f32 v78, v78, 0x3e38aa3b, v254
	v_fmamk_f32 v79, v79, 0x3e38aa3b, v254
	v_exp_f32_e32 v252, v94
	v_mfma_f32_32x32x16_bf16 v[16:31], v[194:197], v[214:217], v[16:31]
	v_exp_f32_e32 v253, v95
	s_nop 0
	v_exp_f32_e32 v232, v78
	v_exp_f32_e32 v233, v79
	s_barrier
	s_waitcnt vmcnt(0)
	v_cndmask_b32_e64 v202, v251, 1.0, s[6:7]
	v_cmp_gt_f32_e32 vcc, 1.0, v202
	s_waitcnt vmcnt(3)
	ds_write_b128 v134, v[112:115]
	s_waitcnt vmcnt(1)
	ds_write_b128 v145, v[124:127]
	ds_write_b128 v175, v[116:119] offset:32768
	s_waitcnt vmcnt(0)
	ds_write_b128 v180, v[120:123] offset:32768
	s_cbranch_vccz .LBB0_219
	s_and_saveexec_b64 s[60:61], s[4:5]
	ds_write_b32 v176, v202 offset:128
	s_or_b64 exec, exec, s[60:61]
	s_waitcnt lgkmcnt(0)
	v_add_u32_e32 v124, v174, v144
	ds_read_b128 v[112:115], v124 offset:224
	ds_read_b128 v[116:119], v124 offset:192
	ds_read_b128 v[120:123], v124 offset:160
	ds_read_b128 v[124:127], v124 offset:128
	s_waitcnt lgkmcnt(3)
	v_pk_mul_f32 v[12:13], v[12:13], v[112:113]
	s_waitcnt lgkmcnt(2)
	v_pk_mul_f32 v[8:9], v[8:9], v[116:117]
	s_waitcnt lgkmcnt(1)
	v_pk_mul_f32 v[4:5], v[4:5], v[120:121]
	v_pk_mul_f32 v[14:15], v[14:15], v[114:115]
	v_pk_mul_f32 v[10:11], v[10:11], v[118:119]
	v_pk_mul_f32 v[6:7], v[6:7], v[122:123]
	s_waitcnt lgkmcnt(0)
	v_pk_mul_f32 v[2:3], v[2:3], v[126:127]
	v_pk_mul_f32 v[0:1], v[0:1], v[124:125]
	v_pk_mul_f32 v[60:61], v[60:61], v[112:113]
	v_pk_mul_f32 v[56:57], v[56:57], v[116:117]
	v_pk_mul_f32 v[52:53], v[52:53], v[120:121]
	v_pk_mul_f32 v[62:63], v[62:63], v[114:115]
	v_pk_mul_f32 v[58:59], v[58:59], v[118:119]
	v_pk_mul_f32 v[54:55], v[54:55], v[122:123]
	v_pk_mul_f32 v[50:51], v[50:51], v[126:127]
	v_pk_mul_f32 v[48:49], v[48:49], v[124:125]
	v_pk_mul_f32 v[44:45], v[44:45], v[112:113]
	v_pk_mul_f32 v[40:41], v[40:41], v[116:117]
	v_pk_mul_f32 v[36:37], v[36:37], v[120:121]
	v_pk_mul_f32 v[46:47], v[46:47], v[114:115]
	v_pk_mul_f32 v[42:43], v[42:43], v[118:119]
	v_pk_mul_f32 v[38:39], v[38:39], v[122:123]
	v_pk_mul_f32 v[34:35], v[34:35], v[126:127]
	v_pk_mul_f32 v[32:33], v[32:33], v[124:125]
	v_pk_mul_f32 v[28:29], v[28:29], v[112:113]
	v_pk_mul_f32 v[24:25], v[24:25], v[116:117]
	v_pk_mul_f32 v[20:21], v[20:21], v[120:121]
	v_pk_mul_f32 v[30:31], v[30:31], v[114:115]
	v_pk_mul_f32 v[26:27], v[26:27], v[118:119]
	v_pk_mul_f32 v[22:23], v[22:23], v[122:123]
	v_pk_mul_f32 v[18:19], v[18:19], v[126:127]
	v_pk_mul_f32 v[16:17], v[16:17], v[124:125]
.LBB0_219:
	s_waitcnt lgkmcnt(0)
	s_barrier
	ds_read_b128 v[64:67], v181 offset:32768
	ds_read_b128 v[68:71], v181 offset:40960
	v_add_f32_e32 v201, 0, v234
	v_add_f32_e32 v201, v235, v201
	v_add_f32_e32 v201, v236, v201
	s_waitcnt lgkmcnt(1)
	v_mfma_f32_32x32x16_bf16 v[80:95], v[64:67], v[108:111], 0
	v_add_f32_e32 v201, v237, v201
	v_add_f32_e32 v201, v238, v201
	ds_read_b128 v[204:207], v182 offset:32768
	ds_read_b128 v[208:211], v182 offset:40960
	v_add_f32_e32 v201, v239, v201
	v_add_f32_e32 v201, v240, v201
	v_add_f32_e32 v201, v241, v201
	v_add_f32_e32 v201, v242, v201
	s_waitcnt lgkmcnt(2)
	v_mfma_f32_32x32x16_bf16 v[64:79], v[68:71], v[108:111], 0
	v_add_f32_e32 v201, v243, v201
	v_add_f32_e32 v201, v244, v201
	v_add_f32_e32 v201, v245, v201
	v_add_f32_e32 v201, v246, v201
	v_add_f32_e32 v201, v247, v201
	v_add_f32_e32 v201, v252, v201
	v_add_f32_e32 v201, v253, v201
	s_waitcnt lgkmcnt(1)
	v_mfma_f32_32x32x16_bf16 v[80:95], v[204:207], v[104:107], v[80:95]
	v_add_f32_e32 v201, v218, v201
	v_add_f32_e32 v201, v219, v201
	v_add_f32_e32 v201, v220, v201
	v_add_f32_e32 v201, v221, v201
	v_add_f32_e32 v201, v222, v201
	v_add_f32_e32 v201, v223, v201
	v_add_f32_e32 v201, v224, v201
	s_waitcnt lgkmcnt(0)
	v_mfma_f32_32x32x16_bf16 v[64:79], v[208:211], v[104:107], v[64:79]
	ds_read_b128 v[204:207], v183 offset:32768
	ds_read_b128 v[208:211], v183 offset:40960
	v_add_f32_e32 v201, v225, v201
	v_add_f32_e32 v201, v226, v201
	v_add_f32_e32 v201, v227, v201
	v_add_f32_e32 v201, v228, v201
	v_add_f32_e32 v201, v229, v201
	v_add_f32_e32 v201, v230, v201
	s_waitcnt lgkmcnt(1)
	v_mfma_f32_32x32x16_bf16 v[80:95], v[204:207], v[100:103], v[80:95]
	v_add_f32_e32 v201, v231, v201
	v_add_f32_e32 v201, v232, v201
	v_add_f32_e32 v203, v233, v201
	s_waitcnt lgkmcnt(0)
	v_mfma_f32_32x32x16_bf16 v[64:79], v[208:211], v[100:103], v[64:79]
	ds_read_b128 v[204:207], v184 offset:32768
	ds_read_b128 v[208:211], v184 offset:40960
	v_cvt_pk_bf16_f32 v128, v234, v235
	v_cvt_pk_bf16_f32 v129, v236, v237
	v_cvt_pk_bf16_f32 v130, v238, v239
	v_cvt_pk_bf16_f32 v131, v240, v241
	v_cvt_pk_bf16_f32 v198, v242, v243
	v_cvt_pk_bf16_f32 v199, v244, v245
	s_waitcnt lgkmcnt(1)
	v_mfma_f32_32x32x16_bf16 v[80:95], v[204:207], v[96:99], v[80:95]
	v_mov_b32_e32 v204, v203
	s_nop 1
	v_permlane32_swap_b32_e32 v203, v204
	v_permlane32_swap_b32_e32 v128, v130
	v_permlane32_swap_b32_e32 v129, v131
	s_waitcnt lgkmcnt(0)
	v_mfma_f32_32x32x16_bf16 v[64:79], v[208:211], v[96:99], v[64:79]
	v_cvt_pk_bf16_f32 v200, v246, v247
	v_cvt_pk_bf16_f32 v201, v252, v253
	v_cvt_pk_bf16_f32 v190, v218, v219
	v_cvt_pk_bf16_f32 v191, v220, v221
	v_cvt_pk_bf16_f32 v192, v222, v223
	v_cvt_pk_bf16_f32 v193, v224, v225
	v_cvt_pk_bf16_f32 v194, v226, v227
	v_cvt_pk_bf16_f32 v195, v228, v229
	v_cvt_pk_bf16_f32 v196, v230, v231
	v_cvt_pk_bf16_f32 v197, v232, v233
	s_nop 0
	v_permlane32_swap_b32_e32 v198, v200
	v_permlane32_swap_b32_e32 v199, v201
	v_permlane32_swap_b32_e32 v190, v192
	v_permlane32_swap_b32_e32 v191, v193
	v_permlane32_swap_b32_e32 v194, v196
	v_permlane32_swap_b32_e32 v195, v197
	v_add_co_u32_e32 v116, vcc, s78, v152
	s_nop 1
	v_addc_co_u32_e32 v117, vcc, 0, v153, vcc
	v_add_co_u32_e32 v120, vcc, s78, v150
	s_nop 1
	v_addc_co_u32_e32 v121, vcc, 0, v151, vcc
	global_load_dwordx4 v[112:115], v[116:117], off offset:1024
	s_nop 0
	global_load_dwordx4 v[116:119], v[116:117], off
	s_nop 0
	global_load_dwordx4 v[124:127], v[120:121], off offset:1024
	s_nop 0
	global_load_dwordx4 v[120:123], v[120:121], off
	ds_read_b64_tr_b16 v[150:151], v179 offset:0
	ds_read_b64_tr_b16 v[152:153], v179 offset:0x800
	ds_read_b64_tr_b16 v[206:207], v179 offset:0x1000
	ds_read_b64_tr_b16 v[208:209], v179 offset:0x1800
	ds_read_b64_tr_b16 v[210:211], v179 offset:0x2000
	ds_read_b64_tr_b16 v[212:213], v179 offset:0x2800
	ds_read_b64_tr_b16 v[214:215], v179 offset:0x3000
	ds_read_b64_tr_b16 v[216:217], v179 offset:0x3800
	s_waitcnt lgkmcnt(0)
	s_nop 0
	v_mfma_f32_32x32x16_bf16 v[0:15], v[128:131], v[150:153], v[0:15]
	ds_read_b64_tr_b16 v[150:151], v179 offset:0x200
	ds_read_b64_tr_b16 v[152:153], v179 offset:0xa00
	v_max_f32_e32 v250, v81, v81
	v_max_f32_e32 v251, v80, v80
	v_max_f32_e32 v250, v251, v250
	v_max3_f32 v250, v250, v82, v83
	v_max3_f32 v250, v250, v84, v85
	v_max3_f32 v250, v250, v86, v87
	v_max3_f32 v250, v250, v88, v89
	v_max3_f32 v250, v250, v90, v91
	v_max3_f32 v250, v250, v92, v93
	v_mfma_f32_32x32x16_bf16 v[0:15], v[198:201], v[206:209], v[0:15]
	ds_read_b64_tr_b16 v[206:207], v179 offset:0x1200
	ds_read_b64_tr_b16 v[208:209], v179 offset:0x1a00
	v_max3_f32 v250, v250, v94, v95
	v_max3_f32 v250, v250, v64, v65
	v_max3_f32 v250, v250, v66, v67
	v_max3_f32 v250, v250, v68, v69
	v_max3_f32 v250, v250, v70, v71
	v_max3_f32 v250, v250, v72, v73
	v_max3_f32 v250, v250, v74, v75
	v_max3_f32 v250, v250, v76, v77
	v_max3_f32 v250, v250, v78, v79
	v_mfma_f32_32x32x16_bf16 v[0:15], v[190:193], v[210:213], v[0:15]
	ds_read_b64_tr_b16 v[210:211], v179 offset:0x2200
	ds_read_b64_tr_b16 v[212:213], v179 offset:0x2a00
	v_mov_b32_e32 v251, v250
	s_nop 1
	v_permlane32_swap_b32_e32 v250, v251
	v_max_f32_e32 v251, v251, v251
	v_max_f32_e32 v250, v250, v250
	v_max_f32_e32 v250, v250, v251
	v_sub_f32_e32 v251, v250, v186
	v_cmp_ge_f32_e32 vcc, s33, v251
	v_max_f32_e32 v251, v186, v186
	v_max_f32_e32 v251, v251, v250
	v_mfma_f32_32x32x16_bf16 v[0:15], v[194:197], v[214:217], v[0:15]
	ds_read_b64_tr_b16 v[214:215], v179 offset:0x3200
	ds_read_b64_tr_b16 v[216:217], v179 offset:0x3a00
	v_sub_f32_e32 v250, v186, v251
	v_mul_f32_e32 v250, 0x3e38aa3b, v250
	v_exp_f32_e32 v250, v250
	s_cmp_eq_u64 vcc, exec
	s_cselect_b64 s[6:7], -1, 0
	v_cndmask_b32_e64 v186, v251, v186, s[6:7]
	v_mul_f32_e32 v254, 0xbe38aa3b, v186
	s_waitcnt lgkmcnt(0)
	v_mfma_f32_32x32x16_bf16 v[48:63], v[128:131], v[150:153], v[48:63]
	ds_read_b64_tr_b16 v[150:151], v179 offset:0x400
	ds_read_b64_tr_b16 v[152:153], v179 offset:0xc00
	v_fmamk_f32 v80, v80, 0x3e38aa3b, v254
	v_fmamk_f32 v81, v81, 0x3e38aa3b, v254
	v_fmamk_f32 v64, v64, 0x3e38aa3b, v254
	v_fmamk_f32 v65, v65, 0x3e38aa3b, v254
	v_exp_f32_e32 v234, v80
	v_exp_f32_e32 v235, v81
	v_fmamk_f32 v82, v82, 0x3e38aa3b, v254
	v_fmamk_f32 v83, v83, 0x3e38aa3b, v254
	v_mfma_f32_32x32x16_bf16 v[48:63], v[198:201], v[206:209], v[48:63]
	ds_read_b64_tr_b16 v[206:207], v179 offset:0x1400
	ds_read_b64_tr_b16 v[208:209], v179 offset:0x1c00
	v_exp_f32_e32 v218, v64
	v_exp_f32_e32 v219, v65
	v_fmamk_f32 v66, v66, 0x3e38aa3b, v254
	v_fmamk_f32 v67, v67, 0x3e38aa3b, v254
	v_exp_f32_e32 v236, v82
	v_mfma_f32_32x32x16_bf16 v[48:63], v[190:193], v[210:213], v[48:63]
	ds_read_b64_tr_b16 v[210:211], v179 offset:0x2400
	ds_read_b64_tr_b16 v[212:213], v179 offset:0x2c00
	v_exp_f32_e32 v237, v83
	v_fmamk_f32 v84, v84, 0x3e38aa3b, v254
	v_fmamk_f32 v85, v85, 0x3e38aa3b, v254
	v_exp_f32_e32 v220, v66
	v_exp_f32_e32 v221, v67
	v_mfma_f32_32x32x16_bf16 v[48:63], v[194:197], v[214:217], v[48:63]
	ds_read_b64_tr_b16 v[214:215], v179 offset:0x3400
	ds_read_b64_tr_b16 v[216:217], v179 offset:0x3c00
	v_fmamk_f32 v68, v68, 0x3e38aa3b, v254
	v_fmamk_f32 v69, v69, 0x3e38aa3b, v254
	v_exp_f32_e32 v238, v84
	v_exp_f32_e32 v239, v85
	v_fmamk_f32 v86, v86, 0x3e38aa3b, v254
	v_fmamk_f32 v87, v87, 0x3e38aa3b, v254
	s_waitcnt lgkmcnt(0)
	v_mfma_f32_32x32x16_bf16 v[32:47], v[128:131], v[150:153], v[32:47]
	ds_read_b64_tr_b16 v[150:151], v179 offset:0x600
	ds_read_b64_tr_b16 v[152:153], v179 offset:0xe00
	v_exp_f32_e32 v222, v68
	v_exp_f32_e32 v223, v69
	v_fmamk_f32 v70, v70, 0x3e38aa3b, v254
	v_fmamk_f32 v71, v71, 0x3e38aa3b, v254
	v_exp_f32_e32 v240, v86
	v_mfma_f32_32x32x16_bf16 v[32:47], v[198:201], v[206:209], v[32:47]
	ds_read_b64_tr_b16 v[206:207], v179 offset:0x1600
	ds_read_b64_tr_b16 v[208:209], v179 offset:0x1e00
	v_exp_f32_e32 v241, v87
	v_fmamk_f32 v88, v88, 0x3e38aa3b, v254
	v_fmamk_f32 v89, v89, 0x3e38aa3b, v254
	v_exp_f32_e32 v224, v70
	v_exp_f32_e32 v225, v71
	v_mfma_f32_32x32x16_bf16 v[32:47], v[190:193], v[210:213], v[32:47]
	ds_read_b64_tr_b16 v[210:211], v179 offset:0x2600
	ds_read_b64_tr_b16 v[212:213], v179 offset:0x2e00
	v_fmamk_f32 v72, v72, 0x3e38aa3b, v254
	v_fmamk_f32 v73, v73, 0x3e38aa3b, v254
	v_exp_f32_e32 v242, v88
	v_exp_f32_e32 v243, v89
	v_fmamk_f32 v90, v90, 0x3e38aa3b, v254
	v_fmamk_f32 v91, v91, 0x3e38aa3b, v254
	v_mfma_f32_32x32x16_bf16 v[32:47], v[194:197], v[214:217], v[32:47]
	ds_read_b64_tr_b16 v[214:215], v179 offset:0x3600
	ds_read_b64_tr_b16 v[216:217], v179 offset:0x3e00
	v_exp_f32_e32 v226, v72
	v_exp_f32_e32 v227, v73
	v_fmamk_f32 v74, v74, 0x3e38aa3b, v254
	v_fmamk_f32 v75, v75, 0x3e38aa3b, v254
	v_exp_f32_e32 v244, v90
	s_waitcnt lgkmcnt(0)
	v_mfma_f32_32x32x16_bf16 v[16:31], v[128:131], v[150:153], v[16:31]
	v_exp_f32_e32 v245, v91
	v_fmamk_f32 v92, v92, 0x3e38aa3b, v254
	v_fmamk_f32 v93, v93, 0x3e38aa3b, v254
	v_exp_f32_e32 v228, v74
	v_exp_f32_e32 v229, v75
	v_mfma_f32_32x32x16_bf16 v[16:31], v[198:201], v[206:209], v[16:31]
	v_fmamk_f32 v76, v76, 0x3e38aa3b, v254
	v_fmamk_f32 v77, v77, 0x3e38aa3b, v254
	v_exp_f32_e32 v246, v92
	v_exp_f32_e32 v247, v93
	v_fmamk_f32 v94, v94, 0x3e38aa3b, v254
	v_fmamk_f32 v95, v95, 0x3e38aa3b, v254
	v_mfma_f32_32x32x16_bf16 v[16:31], v[190:193], v[210:213], v[16:31]
	v_exp_f32_e32 v230, v76
	v_exp_f32_e32 v231, v77
	v_fmamk_f32 v78, v78, 0x3e38aa3b, v254
	v_fmamk_f32 v79, v79, 0x3e38aa3b, v254
	v_exp_f32_e32 v252, v94
	v_mfma_f32_32x32x16_bf16 v[16:31], v[194:197], v[214:217], v[16:31]
	v_exp_f32_e32 v253, v95
	s_nop 0
	v_exp_f32_e32 v232, v78
	v_exp_f32_e32 v233, v79
	s_barrier
	s_waitcnt vmcnt(0)
	v_cndmask_b32_e64 v128, v250, 1.0, s[6:7]
	v_cmp_gt_f32_e32 vcc, 1.0, v128
	s_waitcnt vmcnt(3)
	ds_write_b128 v134, v[112:115] offset:16384
	s_waitcnt vmcnt(1)
	ds_write_b128 v145, v[124:127] offset:16384
	ds_write_b128 v175, v[116:119] offset:49152
	s_waitcnt vmcnt(0)
	ds_write_b128 v180, v[120:123] offset:49152
	s_cbranch_vccz .LBB0_223
	s_and_saveexec_b64 s[60:61], s[4:5]
	ds_write_b32 v176, v128 offset:128
	s_or_b64 exec, exec, s[60:61]
	s_waitcnt lgkmcnt(0)
	v_add_u32_e32 v124, v174, v144
	ds_read_b128 v[112:115], v124 offset:224
	ds_read_b128 v[116:119], v124 offset:192
	ds_read_b128 v[120:123], v124 offset:160
	ds_read_b128 v[124:127], v124 offset:128
	s_waitcnt lgkmcnt(3)
	v_pk_mul_f32 v[12:13], v[12:13], v[112:113]
	s_waitcnt lgkmcnt(2)
	v_pk_mul_f32 v[8:9], v[8:9], v[116:117]
	s_waitcnt lgkmcnt(1)
	v_pk_mul_f32 v[4:5], v[4:5], v[120:121]
	v_pk_mul_f32 v[14:15], v[14:15], v[114:115]
	v_pk_mul_f32 v[10:11], v[10:11], v[118:119]
	v_pk_mul_f32 v[6:7], v[6:7], v[122:123]
	s_waitcnt lgkmcnt(0)
	v_pk_mul_f32 v[2:3], v[2:3], v[126:127]
	v_pk_mul_f32 v[0:1], v[0:1], v[124:125]
	v_pk_mul_f32 v[60:61], v[60:61], v[112:113]
	v_pk_mul_f32 v[56:57], v[56:57], v[116:117]
	v_pk_mul_f32 v[52:53], v[52:53], v[120:121]
	v_pk_mul_f32 v[62:63], v[62:63], v[114:115]
	v_pk_mul_f32 v[58:59], v[58:59], v[118:119]
	v_pk_mul_f32 v[54:55], v[54:55], v[122:123]
	v_pk_mul_f32 v[50:51], v[50:51], v[126:127]
	v_pk_mul_f32 v[48:49], v[48:49], v[124:125]
	v_pk_mul_f32 v[44:45], v[44:45], v[112:113]
	v_pk_mul_f32 v[40:41], v[40:41], v[116:117]
	v_pk_mul_f32 v[36:37], v[36:37], v[120:121]
	v_pk_mul_f32 v[46:47], v[46:47], v[114:115]
	v_pk_mul_f32 v[42:43], v[42:43], v[118:119]
	v_pk_mul_f32 v[38:39], v[38:39], v[122:123]
	v_pk_mul_f32 v[34:35], v[34:35], v[126:127]
	v_pk_mul_f32 v[32:33], v[32:33], v[124:125]
	v_pk_mul_f32 v[28:29], v[28:29], v[112:113]
	v_pk_mul_f32 v[24:25], v[24:25], v[116:117]
	v_pk_mul_f32 v[20:21], v[20:21], v[120:121]
	v_pk_mul_f32 v[30:31], v[30:31], v[114:115]
	v_pk_mul_f32 v[26:27], v[26:27], v[118:119]
	v_pk_mul_f32 v[22:23], v[22:23], v[122:123]
	v_pk_mul_f32 v[18:19], v[18:19], v[126:127]
	v_pk_mul_f32 v[16:17], v[16:17], v[124:125]
.LBB0_223:
	v_add_f32_e32 v64, v187, v188
	s_add_u32 s58, s58, 0xd8000
	v_fmac_f32_e32 v64, v185, v178
	v_add_f32_e32 v178, v203, v204
	s_addc_u32 s59, s59, 0
	s_add_i32 s57, s57, 2
	v_fmac_f32_e32 v178, v64, v202
	s_cmpk_gt_u32 s57, 0x7c
	s_waitcnt lgkmcnt(0)
	s_barrier
	s_cbranch_scc1 .LBB0_225
	v_mov_b32_e32 v185, v128
	s_branch .LBB0_215
.LBB0_225:
	v_mov_b32_e32 v112, v226
	v_mov_b32_e32 v113, v228
	v_mov_b32_e32 v114, v227
	v_mov_b32_e32 v115, v230
	v_mov_b32_e32 v116, v229
	v_mov_b32_e32 v117, v232
	v_mov_b32_e32 v118, v231
	v_mov_b32_e32 v119, v233
	v_mov_b32_e32 v120, v218
	v_mov_b32_e32 v121, v220
	v_mov_b32_e32 v122, v219
	v_mov_b32_e32 v123, v222
	v_mov_b32_e32 v124, v221
	v_mov_b32_e32 v125, v224
	v_mov_b32_e32 v126, v223
	v_mov_b32_e32 v127, v225
	v_mov_b32_e32 v129, v234
	v_mov_b32_e32 v130, v236
	v_mov_b32_e32 v131, v235
	v_mov_b32_e32 v189, v242
	v_mov_b32_e32 v190, v244
	v_mov_b32_e32 v191, v252
	v_mov_b32_e32 v192, v243
	v_mov_b32_e32 v193, v246
	v_mov_b32_e32 v194, v245
	v_mov_b32_e32 v195, v253
	v_mov_b32_e32 v196, v247
	v_mov_b32_e32 v197, v238
	v_mov_b32_e32 v198, v237
	v_mov_b32_e32 v199, v240
	v_mov_b32_e32 v200, v239
	v_mov_b32_e32 v201, v241
	ds_read_b128 v[64:67], v181 offset:49152
	ds_read_b128 v[68:71], v181 offset:57344
	s_waitcnt lgkmcnt(1)
	v_mfma_f32_32x32x16_bf16 v[80:95], v[64:67], v[108:111], 0
	s_waitcnt lgkmcnt(0)
	v_mfma_f32_32x32x16_bf16 v[64:79], v[68:71], v[108:111], 0
	ds_read_b128 v[108:111], v182 offset:49152
	ds_read_b128 v[146:149], v182 offset:57344
	s_waitcnt lgkmcnt(1)
	v_mfma_f32_32x32x16_bf16 v[80:95], v[108:111], v[104:107], v[80:95]
	s_waitcnt lgkmcnt(0)
	v_mfma_f32_32x32x16_bf16 v[64:79], v[146:149], v[104:107], v[64:79]
	ds_read_b128 v[104:107], v183 offset:49152
	ds_read_b128 v[108:111], v183 offset:57344
	s_waitcnt lgkmcnt(1)
	v_mfma_f32_32x32x16_bf16 v[80:95], v[104:107], v[100:103], v[80:95]
	s_waitcnt lgkmcnt(0)
	v_mfma_f32_32x32x16_bf16 v[64:79], v[108:111], v[100:103], v[64:79]
	ds_read_b128 v[100:103], v184 offset:49152
	ds_read_b128 v[104:107], v184 offset:57344
	s_waitcnt lgkmcnt(1)
	v_mfma_f32_32x32x16_bf16 v[80:95], v[100:103], v[96:99], v[80:95]
	s_waitcnt lgkmcnt(0)
	v_mfma_f32_32x32x16_bf16 v[64:79], v[104:107], v[96:99], v[64:79]
	v_add_f32_e32 v96, 0, v129
	v_add_f32_e32 v96, v131, v96
	v_add_f32_e32 v96, v130, v96
	v_add_f32_e32 v96, v198, v96
	v_add_f32_e32 v96, v197, v96
	v_add_f32_e32 v96, v200, v96
	v_add_f32_e32 v96, v199, v96
	v_add_f32_e32 v96, v201, v96
	v_add_f32_e32 v96, v189, v96
	v_add_f32_e32 v96, v192, v96
	v_add_f32_e32 v96, v190, v96
	v_add_f32_e32 v96, v194, v96
	v_add_f32_e32 v96, v193, v96
	v_add_f32_e32 v96, v196, v96
	v_add_f32_e32 v96, v191, v96
	v_add_f32_e32 v96, v195, v96
	v_add_f32_e32 v96, v120, v96
	v_add_f32_e32 v96, v122, v96
	v_add_f32_e32 v96, v121, v96
	v_add_f32_e32 v96, v124, v96
	v_add_f32_e32 v96, v123, v96
	v_add_f32_e32 v96, v126, v96
	v_add_f32_e32 v96, v125, v96
	v_add_f32_e32 v96, v127, v96
	v_add_f32_e32 v96, v112, v96
	v_add_f32_e32 v96, v114, v96
	v_add_f32_e32 v96, v113, v96
	v_add_f32_e32 v96, v116, v96
	v_add_f32_e32 v96, v115, v96
	v_add_f32_e32 v96, v118, v96
	v_add_f32_e32 v96, v117, v96
	v_add_f32_e32 v100, v119, v96
	v_mov_b32_e32 v101, v100
	v_cvt_pk_bf16_f32 v96, v129, v131
	v_cvt_pk_bf16_f32 v97, v130, v198
	v_cvt_pk_bf16_f32 v98, v197, v200
	v_cvt_pk_bf16_f32 v99, v199, v201
	s_nop 1
	v_permlane32_swap_b32_e32 v100, v101
	v_permlane32_swap_b32_e32 v96, v98
	v_permlane32_swap_b32_e32 v97, v99
	v_cvt_pk_bf16_f32 v102, v189, v192
	v_cvt_pk_bf16_f32 v103, v190, v194
	v_cvt_pk_bf16_f32 v104, v193, v196
	v_cvt_pk_bf16_f32 v105, v191, v195
	v_cvt_pk_bf16_f32 v106, v120, v122
	v_cvt_pk_bf16_f32 v107, v121, v124
	v_cvt_pk_bf16_f32 v108, v123, v126
	v_cvt_pk_bf16_f32 v109, v125, v127
	v_cvt_pk_bf16_f32 v110, v112, v114
	v_cvt_pk_bf16_f32 v111, v113, v116
	v_cvt_pk_bf16_f32 v112, v115, v118
	v_cvt_pk_bf16_f32 v113, v117, v119
	s_nop 0
	v_permlane32_swap_b32_e32 v102, v104
	v_permlane32_swap_b32_e32 v103, v105
	v_permlane32_swap_b32_e32 v106, v108
	v_permlane32_swap_b32_e32 v107, v109
	v_permlane32_swap_b32_e32 v110, v112
	v_permlane32_swap_b32_e32 v111, v113
	ds_read_b64_tr_b16 v[114:115], v177 offset:0
	ds_read_b64_tr_b16 v[116:117], v177 offset:0x800
	ds_read_b64_tr_b16 v[118:119], v177 offset:0x1000
	ds_read_b64_tr_b16 v[120:121], v177 offset:0x1800
	ds_read_b64_tr_b16 v[122:123], v177 offset:0x2000
	ds_read_b64_tr_b16 v[124:125], v177 offset:0x2800
	ds_read_b64_tr_b16 v[146:147], v177 offset:0x3000
	ds_read_b64_tr_b16 v[148:149], v177 offset:0x3800
	s_waitcnt lgkmcnt(0)
	s_nop 0
	v_mfma_f32_32x32x16_bf16 v[0:15], v[96:99], v[114:117], v[0:15]
	ds_read_b64_tr_b16 v[114:115], v177 offset:0x200
	ds_read_b64_tr_b16 v[116:117], v177 offset:0xa00
	v_mfma_f32_32x32x16_bf16 v[0:15], v[102:105], v[118:121], v[0:15]
	ds_read_b64_tr_b16 v[118:119], v177 offset:0x1200
	ds_read_b64_tr_b16 v[120:121], v177 offset:0x1a00
	v_mfma_f32_32x32x16_bf16 v[0:15], v[106:109], v[122:125], v[0:15]
	ds_read_b64_tr_b16 v[122:123], v177 offset:0x2200
	ds_read_b64_tr_b16 v[124:125], v177 offset:0x2a00
	v_mfma_f32_32x32x16_bf16 v[0:15], v[110:113], v[146:149], v[0:15]
	ds_read_b64_tr_b16 v[146:147], v177 offset:0x3200
	ds_read_b64_tr_b16 v[148:149], v177 offset:0x3a00
	s_waitcnt lgkmcnt(0)
	v_mfma_f32_32x32x16_bf16 v[48:63], v[96:99], v[114:117], v[48:63]
	ds_read_b64_tr_b16 v[114:115], v177 offset:0x400
	ds_read_b64_tr_b16 v[116:117], v177 offset:0xc00
	v_mfma_f32_32x32x16_bf16 v[48:63], v[102:105], v[118:121], v[48:63]
	ds_read_b64_tr_b16 v[118:119], v177 offset:0x1400
	ds_read_b64_tr_b16 v[120:121], v177 offset:0x1c00
	v_mfma_f32_32x32x16_bf16 v[48:63], v[106:109], v[122:125], v[48:63]
	ds_read_b64_tr_b16 v[122:123], v177 offset:0x2400
	ds_read_b64_tr_b16 v[124:125], v177 offset:0x2c00
	v_mfma_f32_32x32x16_bf16 v[48:63], v[110:113], v[146:149], v[48:63]
	ds_read_b64_tr_b16 v[146:147], v177 offset:0x3400
	ds_read_b64_tr_b16 v[148:149], v177 offset:0x3c00
	s_waitcnt lgkmcnt(0)
	v_mfma_f32_32x32x16_bf16 v[32:47], v[96:99], v[114:117], v[32:47]
	ds_read_b64_tr_b16 v[114:115], v177 offset:0x600
	ds_read_b64_tr_b16 v[116:117], v177 offset:0xe00
	v_mfma_f32_32x32x16_bf16 v[32:47], v[102:105], v[118:121], v[32:47]
	ds_read_b64_tr_b16 v[118:119], v177 offset:0x1600
	ds_read_b64_tr_b16 v[120:121], v177 offset:0x1e00
	v_mfma_f32_32x32x16_bf16 v[32:47], v[106:109], v[122:125], v[32:47]
	ds_read_b64_tr_b16 v[122:123], v177 offset:0x2600
	ds_read_b64_tr_b16 v[124:125], v177 offset:0x2e00
	v_mfma_f32_32x32x16_bf16 v[32:47], v[110:113], v[146:149], v[32:47]
	ds_read_b64_tr_b16 v[146:147], v177 offset:0x3600
	ds_read_b64_tr_b16 v[148:149], v177 offset:0x3e00
	s_waitcnt lgkmcnt(0)
	v_mfma_f32_32x32x16_bf16 v[16:31], v[96:99], v[114:117], v[16:31]
	v_max_f32_e32 v96, v81, v81
	v_max_f32_e32 v97, v80, v80
	v_max_f32_e32 v96, v97, v96
	v_max3_f32 v96, v96, v82, v83
	v_max3_f32 v96, v96, v84, v85
	v_max3_f32 v96, v96, v86, v87
	v_max3_f32 v96, v96, v88, v89
	v_max3_f32 v96, v96, v90, v91
	v_max3_f32 v96, v96, v92, v93
	v_mfma_f32_32x32x16_bf16 v[16:31], v[102:105], v[118:121], v[16:31]
	v_max3_f32 v96, v96, v94, v95
	v_max3_f32 v96, v96, v64, v65
	v_max3_f32 v96, v96, v66, v67
	v_max3_f32 v96, v96, v68, v69
	v_max3_f32 v96, v96, v70, v71
	v_max3_f32 v96, v96, v72, v73
	v_max3_f32 v96, v96, v74, v75
	v_max3_f32 v96, v96, v76, v77
	v_mfma_f32_32x32x16_bf16 v[16:31], v[106:109], v[122:125], v[16:31]
	v_max3_f32 v96, v96, v78, v79
	v_mov_b32_e32 v97, v96
	s_nop 1
	v_permlane32_swap_b32_e32 v96, v97
	v_max_f32_e32 v97, v97, v97
	v_max_f32_e32 v96, v96, v96
	v_max_f32_e32 v96, v96, v97
	v_sub_f32_e32 v97, v96, v186
	v_cmp_ge_f32_e32 vcc, s33, v97
	v_max_f32_e32 v97, v186, v186
	v_max_f32_e32 v97, v97, v96
	v_mfma_f32_32x32x16_bf16 v[16:31], v[110:113], v[146:149], v[16:31]
	v_sub_f32_e32 v96, v186, v97
	v_mul_f32_e32 v96, 0x3e38aa3b, v96
	v_exp_f32_e32 v96, v96
	s_cmp_eq_u64 vcc, exec
	s_cselect_b64 s[6:7], -1, 0
	v_cndmask_b32_e64 v96, v96, 1.0, s[6:7]
	v_cmp_gt_f32_e32 vcc, 1.0, v96
	s_barrier
	s_cbranch_vccz .LBB0_229
	s_and_saveexec_b64 s[58:59], s[4:5]
	ds_write_b32 v176, v96 offset:128
	s_or_b64 exec, exec, s[58:59]
	s_waitcnt lgkmcnt(0)
	v_add_u32_e32 v98, v174, v144
	ds_read_b128 v[102:105], v98 offset:224
	ds_read_b128 v[106:109], v98 offset:192
	ds_read_b128 v[110:113], v98 offset:160
	ds_read_b128 v[114:117], v98 offset:128
	s_waitcnt lgkmcnt(3)
	v_pk_mul_f32 v[12:13], v[12:13], v[102:103]
	s_waitcnt lgkmcnt(2)
	v_pk_mul_f32 v[8:9], v[8:9], v[106:107]
	s_waitcnt lgkmcnt(1)
	v_pk_mul_f32 v[4:5], v[4:5], v[110:111]
	v_pk_mul_f32 v[14:15], v[14:15], v[104:105]
	v_pk_mul_f32 v[10:11], v[10:11], v[108:109]
	v_pk_mul_f32 v[6:7], v[6:7], v[112:113]
	s_waitcnt lgkmcnt(0)
	v_pk_mul_f32 v[2:3], v[2:3], v[116:117]
	v_pk_mul_f32 v[0:1], v[0:1], v[114:115]
	v_pk_mul_f32 v[60:61], v[60:61], v[102:103]
	v_pk_mul_f32 v[56:57], v[56:57], v[106:107]
	v_pk_mul_f32 v[52:53], v[52:53], v[110:111]
	v_pk_mul_f32 v[62:63], v[62:63], v[104:105]
	v_pk_mul_f32 v[58:59], v[58:59], v[108:109]
	v_pk_mul_f32 v[54:55], v[54:55], v[112:113]
	v_pk_mul_f32 v[50:51], v[50:51], v[116:117]
	v_pk_mul_f32 v[48:49], v[48:49], v[114:115]
	v_pk_mul_f32 v[44:45], v[44:45], v[102:103]
	v_pk_mul_f32 v[40:41], v[40:41], v[106:107]
	v_pk_mul_f32 v[36:37], v[36:37], v[110:111]
	v_pk_mul_f32 v[46:47], v[46:47], v[104:105]
	v_pk_mul_f32 v[42:43], v[42:43], v[108:109]
	v_pk_mul_f32 v[38:39], v[38:39], v[112:113]
	v_pk_mul_f32 v[34:35], v[34:35], v[116:117]
	v_pk_mul_f32 v[32:33], v[32:33], v[114:115]
	v_pk_mul_f32 v[28:29], v[28:29], v[102:103]
	v_pk_mul_f32 v[24:25], v[24:25], v[106:107]
	v_pk_mul_f32 v[20:21], v[20:21], v[110:111]
	v_pk_mul_f32 v[30:31], v[30:31], v[104:105]
	v_pk_mul_f32 v[26:27], v[26:27], v[108:109]
	v_pk_mul_f32 v[22:23], v[22:23], v[112:113]
	v_pk_mul_f32 v[18:19], v[18:19], v[116:117]
	v_pk_mul_f32 v[16:17], v[16:17], v[114:115]
